# combo1 + next-row prefetch in the two MODE-0 norm/modulate row loops
# speedup vs baseline: 1.0045x; 1.0045x over previous
; template <int MODE, bool SRC32>
; __device__ __forceinline__ void phase_mod(const float* x32, _Float16* xh, float* out32, bf16* h, const float* gprev, const float* gain, const float* shiftv, const float* scalev, int wave, int lane) {
;     const int blk = (int)blockIdx.x, b = blk >> 5, r0 = blk * 128 + wave * 16;
;     f32x4 A[8], Sh[8], G3[8];
; #pragma unroll
;     for (int k = 0; k < 8; ++k) {
;         const int d = 512 * (k >> 1) + 8 * lane + 4 * (k & 1);
;         if (MODE != 2) { const f32x4 g = *(const f32x4*)(gain + d), sc = *(const f32x4*)(scalev + (size_t)b * NMOD + d); A[k] = g * (sc + 1.0f); Sh[k] = *(const f32x4*)(shiftv + (size_t)b * NMOD + d); }
;         if (MODE != 0) G3[k] = *(const f32x4*)(gprev + d);
;     }
;     for (int i = 0; i < 16; ++i) {
;         const size_t ro = (size_t)(r0 + i) * D + 8 * lane;
.LBB0_289:
	s_cmp_le_i32 s44, s27
	s_cselect_b64 s[0:1], -1, 0
	s_cmp_lt_i32 s27, s45
	s_cselect_b64 s[6:7], -1, 0
	s_and_b64 s[6:7], s[0:1], s[6:7]
	s_andn2_b64 vcc, exec, s[6:7]
	v_readfirstlane_b32 s0, v214
	s_cbranch_vccnz .LBB0_293
	s_ashr_i32 s0, s0, 2
	s_and_b32 s0, s0, -16
	v_readlane_b32 s1, v253, 7
	s_add_i32 s8, s0, s1
	v_readlane_b32 s0, v254, 44
	v_readlane_b32 s1, v254, 45
	s_lshl_b64 s[0:1], s[0:1], 2
	s_add_u32 s9, s55, s0
	s_addc_u32 s11, s60, s1
	s_add_u32 s0, s9, 0x6000
	s_addc_u32 s1, s11, 0
	s_add_u32 s10, s9, 0x8000
	s_addc_u32 s11, s11, 0
	s_add_u32 s12, s20, 0x2000
	v_lshlrev_b32_e32 v0, 5, v214
	s_addc_u32 s13, s21, 0
	v_and_b32_e32 v24, 0x7e0, v0
	global_load_dwordx4 v[8:11], v24, s[12:13] offset:16
	global_load_dwordx4 v[0:3], v24, s[12:13]
	global_load_dwordx4 v[12:15], v24, s[10:11] offset:16
	global_load_dwordx4 v[4:7], v24, s[10:11]
	v_or_b32_e32 v20, 0x800, v24
	v_or_b32_e32 v52, 0x1000, v24
	v_or_b32_e32 v60, 0x1800, v24
	v_cmp_lt_i32_e32 vcc, v222, v216
	s_ashr_i32 s9, s8, 31
	s_waitcnt vmcnt(0)
	v_pk_add_f32 v[14:15], v[14:15], 1.0 op_sel_hi:[1,0]
	v_pk_add_f32 v[6:7], v[6:7], 1.0 op_sel_hi:[1,0]
	v_pk_add_f32 v[4:5], v[4:5], 1.0 op_sel_hi:[1,0]
	v_pk_add_f32 v[12:13], v[12:13], 1.0 op_sel_hi:[1,0]
	v_pk_mul_f32 v[32:33], v[2:3], v[6:7]
	v_pk_mul_f32 v[34:35], v[0:1], v[4:5]
	global_load_dwordx4 v[0:3], v24, s[0:1] offset:16
	global_load_dwordx4 v[4:7], v24, s[0:1]
	v_pk_mul_f32 v[36:37], v[10:11], v[14:15]
	v_pk_mul_f32 v[38:39], v[8:9], v[12:13]
	global_load_dwordx4 v[16:19], v20, s[12:13] offset:16
	global_load_dwordx4 v[8:11], v20, s[12:13]
	s_nop 0
	global_load_dwordx4 v[20:23], v24, s[10:11] offset:2064
	global_load_dwordx4 v[12:15], v24, s[10:11] offset:2048
	s_waitcnt vmcnt(1)
	v_pk_add_f32 v[22:23], v[22:23], 1.0 op_sel_hi:[1,0]
	s_waitcnt vmcnt(0)
	v_pk_add_f32 v[14:15], v[14:15], 1.0 op_sel_hi:[1,0]
	v_pk_add_f32 v[12:13], v[12:13], 1.0 op_sel_hi:[1,0]
	v_pk_add_f32 v[20:21], v[20:21], 1.0 op_sel_hi:[1,0]
	v_pk_mul_f32 v[40:41], v[10:11], v[14:15]
	v_pk_mul_f32 v[42:43], v[8:9], v[12:13]
	global_load_dwordx4 v[8:11], v24, s[0:1] offset:2064
	global_load_dwordx4 v[12:15], v24, s[0:1] offset:2048
	v_pk_mul_f32 v[44:45], v[18:19], v[22:23]
	v_pk_mul_f32 v[46:47], v[16:17], v[20:21]
	global_load_dwordx4 v[24:27], v52, s[12:13] offset:16
	global_load_dwordx4 v[16:19], v52, s[12:13]
	global_load_dwordx4 v[28:31], v52, s[10:11] offset:16
	global_load_dwordx4 v[20:23], v52, s[10:11]
	s_waitcnt vmcnt(1)
	v_pk_add_f32 v[30:31], v[30:31], 1.0 op_sel_hi:[1,0]
	s_waitcnt vmcnt(0)
	v_pk_add_f32 v[22:23], v[22:23], 1.0 op_sel_hi:[1,0]
	v_pk_add_f32 v[20:21], v[20:21], 1.0 op_sel_hi:[1,0]
	v_pk_add_f32 v[28:29], v[28:29], 1.0 op_sel_hi:[1,0]
	v_pk_mul_f32 v[48:49], v[18:19], v[22:23]
	v_pk_mul_f32 v[50:51], v[16:17], v[20:21]
	global_load_dwordx4 v[16:19], v52, s[0:1] offset:16
	global_load_dwordx4 v[20:23], v52, s[0:1]
	v_pk_mul_f32 v[52:53], v[26:27], v[30:31]
	v_pk_mul_f32 v[54:55], v[24:25], v[28:29]
	global_load_dwordx4 v[62:65], v60, s[12:13] offset:16
	global_load_dwordx4 v[24:27], v60, s[12:13]
	global_load_dwordx4 v[66:69], v60, s[10:11] offset:16
	global_load_dwordx4 v[28:31], v60, s[10:11]
	s_waitcnt vmcnt(1)
	v_pk_add_f32 v[66:67], v[66:67], 1.0 op_sel_hi:[1,0]
	s_waitcnt vmcnt(0)
	v_pk_add_f32 v[30:31], v[30:31], 1.0 op_sel_hi:[1,0]
	v_pk_add_f32 v[28:29], v[28:29], 1.0 op_sel_hi:[1,0]
	v_pk_mul_f32 v[56:57], v[26:27], v[30:31]
	v_pk_mul_f32 v[58:59], v[24:25], v[28:29]
	global_load_dwordx4 v[24:27], v60, s[0:1] offset:16
	global_load_dwordx4 v[28:31], v60, s[0:1]
	v_pk_add_f32 v[60:61], v[68:69], 1.0 op_sel_hi:[1,0]
	v_pk_mul_f32 v[62:63], v[62:63], v[66:67]
	v_pk_mul_f32 v[60:61], v[64:65], v[60:61]
	v_cndmask_b32_e32 v64, v215, v222, vcc
	v_cmp_lt_i32_e32 vcc, v221, v216
	v_lshlrev_b32_e32 v66, 2, v64
	s_lshl_b64 s[0:1], s[8:9], 12
	v_cndmask_b32_e32 v64, v215, v221, vcc
	v_cmp_lt_i32_e32 vcc, v220, v216
	v_lshlrev_b32_e32 v67, 2, v64
	s_add_u32 s0, s42, s0
	v_cndmask_b32_e32 v64, v215, v220, vcc
	v_cmp_lt_i32_e32 vcc, v219, v216
	v_lshlrev_b32_e32 v68, 2, v64
	s_addc_u32 s1, s43, s1
	v_cndmask_b32_e32 v64, v215, v219, vcc
	v_cmp_lt_i32_e32 vcc, v218, v216
	v_lshlrev_b32_e32 v69, 2, v64
	s_mov_b64 s[8:9], 0
	v_cndmask_b32_e32 v64, v215, v218, vcc
	v_cmp_lt_i32_e32 vcc, v217, v216
	v_lshlrev_b32_e32 v70, 2, v64
	s_nop 0
	v_cndmask_b32_e32 v64, v215, v217, vcc
	v_lshlrev_b32_e32 v71, 2, v64
	v_and_b32_e32 v64, 63, v214
	v_lshlrev_b32_e32 v168, 4, v64
	v_lshl_add_u64 v[64:65], s[0:1], 0, v[168:169]
	v_add_co_u32_e32 v136, vcc, 0x4ae00000, v64
	v_mov_b32_e32 v138, 0x1000
	v_mov_b32_e32 v139, 0
	v_addc_co_u32_e32 v137, vcc, 0, v65, vcc
	global_load_dwordx4 v[120:123], v[136:137], off
	global_load_dwordx4 v[128:131], v[136:137], off offset:2048
	global_load_dwordx4 v[124:127], v[136:137], off offset:1024
	global_load_dwordx4 v[132:135], v[136:137], off offset:3072
	s_waitcnt vmcnt(0)
; template <int MODE, bool SRC32>
; __device__ __forceinline__ void phase_mod(const float* x32, _Float16* xh, float* out32, bf16* h, const float* gprev, const float* gain, const float* shiftv, const float* scalev, int wave, int lane) {
;     ...
;     for (int i = 0; i < 16; ++i) {
;         const size_t ro = (size_t)(r0 + i) * D + 8 * lane;
;         f32x4 v[8]; float ss = 0.f;
; #pragma unroll
;         for (int j = 0; j < 4; ++j) {
;             if (SRC32) { v[2 * j] = *(const f32x4*)(x32 + ro + 512 * j); v[2 * j + 1] = *(const f32x4*)(x32 + ro + 512 * j + 4); }
;             else h8_to_f(*(const h16x8*)(xh + ro + 512 * j), v[2 * j], v[2 * j + 1]);
;         }
; #pragma unroll
;         for (int k = 0; k < 8; ++k) ss += (v[k][0] * v[k][0] + v[k][1] * v[k][1]) + (v[k][2] * v[k][2] + v[k][3] * v[k][3]);
.LBB0_291:
	v_lshl_add_u64 v[84:85], v[64:65], 0, s[8:9]
	s_add_u32 s8, s8, 0x1000
	s_addc_u32 s9, s9, 0
	s_cmp_lg_u32 s8, 0x10000
	s_waitcnt vmcnt(7)
	v_cvt_f32_f16_e32 v86, v120
	v_cvt_f32_f16_sdwa v87, v120 dst_sel:DWORD dst_unused:UNUSED_PAD src0_sel:WORD_1
	v_cvt_f32_f16_e32 v88, v121
	v_cvt_f32_f16_sdwa v89, v121 dst_sel:DWORD dst_unused:UNUSED_PAD src0_sel:WORD_1
	v_cvt_f32_f16_e32 v90, v122
	v_cvt_f32_f16_sdwa v91, v122 dst_sel:DWORD dst_unused:UNUSED_PAD src0_sel:WORD_1
	v_cvt_f32_f16_e32 v92, v123
	v_cvt_f32_f16_sdwa v93, v123 dst_sel:DWORD dst_unused:UNUSED_PAD src0_sel:WORD_1
	v_mov_b32_e32 v104, v87
	v_mov_b32_e32 v105, v91
	v_mov_b32_e32 v102, v86
	v_mov_b32_e32 v103, v90
	v_pk_mul_f32 v[104:105], v[104:105], v[104:105]
	v_mov_b32_e32 v106, v89
	v_mov_b32_e32 v107, v93
	v_pk_fma_f32 v[102:103], v[102:103], v[102:103], v[104:105]
	v_mov_b32_e32 v104, v88
	v_mov_b32_e32 v105, v92
	v_pk_mul_f32 v[106:107], v[106:107], v[106:107]
	s_waitcnt vmcnt(6)
	v_cvt_f32_f16_e32 v96, v128
	v_pk_fma_f32 v[104:105], v[104:105], v[104:105], v[106:107]
	v_cvt_f32_f16_sdwa v97, v128 dst_sel:DWORD dst_unused:UNUSED_PAD src0_sel:WORD_1
	v_pk_add_f32 v[102:103], v[102:103], v[104:105]
	v_cvt_f32_f16_e32 v76, v129
	v_cvt_f32_f16_sdwa v77, v129 dst_sel:DWORD dst_unused:UNUSED_PAD src0_sel:WORD_1
	v_pk_add_f32 v[102:103], v[102:103], v[102:103] op_sel_hi:[0,1]
	v_pk_mul_f32 v[110:111], v[96:97], v[96:97]
	v_pk_mul_f32 v[112:113], v[76:77], v[76:77]
	s_nop 0
	v_mov_b32_e32 v102, v112
	s_waitcnt vmcnt(5)
	v_cvt_f32_f16_sdwa v107, v125 dst_sel:DWORD dst_unused:UNUSED_PAD src0_sel:WORD_1
	v_cvt_f32_f16_sdwa v106, v124 dst_sel:DWORD dst_unused:UNUSED_PAD src0_sel:WORD_1
	v_cvt_f32_f16_e32 v105, v125
	v_cvt_f32_f16_e32 v104, v124
	v_cvt_f32_f16_e32 v108, v127
	v_cvt_f32_f16_e32 v94, v126
	v_pk_mul_f32 v[72:73], v[106:107], v[106:107]
	v_cvt_f32_f16_sdwa v109, v127 dst_sel:DWORD dst_unused:UNUSED_PAD src0_sel:WORD_1
	v_cvt_f32_f16_sdwa v95, v126 dst_sel:DWORD dst_unused:UNUSED_PAD src0_sel:WORD_1
	v_pk_fma_f32 v[72:73], v[104:105], v[104:105], v[72:73]
	s_waitcnt vmcnt(4)
	v_cvt_f32_f16_e32 v98, v132
	v_pk_add_f32 v[72:73], v[72:73], v[72:73] op_sel_hi:[0,1]
	v_mul_f32_e32 v72, v108, v108
	v_pk_fma_f32 v[74:75], v[108:109], v[108:109], v[72:73] op_sel_hi:[1,1,0]
	v_mul_f32_e32 v72, v94, v94
	v_pk_fma_f32 v[114:115], v[94:95], v[94:95], v[72:73] op_sel_hi:[1,1,0]
	v_mov_b32_e32 v72, v113
	v_cvt_f32_f16_sdwa v99, v132 dst_sel:DWORD dst_unused:UNUSED_PAD src0_sel:WORD_1
	v_mov_b32_e32 v114, v110
	v_mov_b32_e32 v74, v111
	v_pk_add_f32 v[72:73], v[102:103], v[72:73]
	v_cvt_f32_f16_e32 v103, v131
	v_cvt_f32_f16_e32 v102, v130
	v_cvt_f32_f16_sdwa v79, v131 dst_sel:DWORD dst_unused:UNUSED_PAD src0_sel:WORD_1
	v_cvt_f32_f16_sdwa v78, v130 dst_sel:DWORD dst_unused:UNUSED_PAD src0_sel:WORD_1
	v_cvt_f32_f16_e32 v80, v133
	v_pk_add_f32 v[74:75], v[114:115], v[74:75]
	v_cvt_f32_f16_sdwa v81, v133 dst_sel:DWORD dst_unused:UNUSED_PAD src0_sel:WORD_1
	v_cvt_f32_f16_e32 v100, v134
	v_cvt_f32_f16_sdwa v101, v134 dst_sel:DWORD dst_unused:UNUSED_PAD src0_sel:WORD_1
	v_cvt_f32_f16_e32 v82, v135
	v_cvt_f32_f16_sdwa v83, v135 dst_sel:DWORD dst_unused:UNUSED_PAD src0_sel:WORD_1
	s_cbranch_scc0 .Lmodpf_b_skip
	v_lshl_add_u64 v[136:137], v[136:137], 0, v[138:139]
	global_load_dwordx4 v[120:123], v[136:137], off
	global_load_dwordx4 v[128:131], v[136:137], off offset:2048
	global_load_dwordx4 v[124:127], v[136:137], off offset:1024
	global_load_dwordx4 v[132:135], v[136:137], off offset:3072
; __device__ __forceinline__ unsigned cvt_pk_bf16(float lo, float hi) { unsigned r; asm volatile("v_cvt_pk_bf16_f32 %0, %1, %2" : "=v"(r) : "v"(lo), "v"(hi)); return r; }
; __device__ __forceinline__ h16x8 f_to_h8(const f32x4 a, const f32x4 b) { return (h16x8){(_Float16)a[0], (_Float16)a[1], (_Float16)a[2], (_Float16)a[3], (_Float16)b[0], (_Float16)b[1], (_Float16)b[2], (_Float16)b[3]}; }
; template <int MODE, bool SRC32>
; __device__ __forceinline__ void phase_mod(const float* x32, _Float16* xh, float* out32, bf16* h, const float* gprev, const float* gain, const float* shiftv, const float* scalev, int wave, int lane) {
;     ...
;         for (int k = 0; k < 8; ++k) ss += (v[k][0] * v[k][0] + v[k][1] * v[k][1]) + (v[k][2] * v[k][2] + v[k][3] * v[k][3]);
;         ss = wave_sum(ss);
;         float rstd = 1.0f / sqrtf(ss * (1.0f / D) + EPS);
;         if (MODE != 0) {
;             float s2 = 0.f;
; #pragma unroll
;             for (int k = 0; k < 8; ++k) { v[k] = v[k] * rstd * G3[k]; s2 += (v[k][0] * v[k][0] + v[k][1] * v[k][1]) + (v[k][2] * v[k][2] + v[k][3] * v[k][3]); }
; #pragma unroll
;             for (int j = 0; j < 4; ++j) {
;                 if (MODE == 1) *(h16x8*)(xh + ro + 512 * j) = f_to_h8(v[2 * j], v[2 * j + 1]);
;                 else { *(f32x4*)(out32 + ro + 512 * j) = v[2 * j]; *(f32x4*)(out32 + ro + 512 * j + 4) = v[2 * j + 1]; }
;             }
;             if (MODE == 2) continue;
;             s2 = wave_sum(s2);
;             rstd = 1.0f / sqrtf(s2 * (1.0f / D) + EPS);
;         }
; #pragma unroll
;         for (int j = 0; j < 4; ++j) { const f32x4 o0 = v[2 * j] * rstd * A[2 * j] + Sh[2 * j], o1 = v[2 * j + 1] * rstd * A[2 * j + 1] + Sh[2 * j + 1];
;             u32x4 w; w.x = cvt_pk_bf16(o0[0], o0[1]); w.y = cvt_pk_bf16(o0[2], o0[3]); w.z = cvt_pk_bf16(o1[0], o1[1]); w.w = cvt_pk_bf16(o1[2], o1[3]);
;             *(u32x4*)(h + ro + 512 * j) = w; }
;     }
.Lmodpf_b_skip:
	v_pk_add_f32 v[72:73], v[74:75], v[72:73]
	v_pk_mul_f32 v[74:75], v[78:79], v[78:79]
	v_pk_add_f32 v[72:73], v[72:73], v[72:73] op_sel_hi:[0,1]
	v_mul_f32_e32 v72, v80, v80
	v_pk_fma_f32 v[74:75], v[102:103], v[102:103], v[74:75]
	v_pk_fma_f32 v[110:111], v[80:81], v[80:81], v[72:73] op_sel_hi:[1,1,0]
	v_mul_f32_e32 v72, v98, v98
	v_pk_add_f32 v[74:75], v[74:75], v[74:75] op_sel_hi:[0,1]
	v_pk_mul_f32 v[112:113], v[100:101], v[100:101]
	v_pk_mul_f32 v[114:115], v[82:83], v[82:83]
	v_pk_fma_f32 v[116:117], v[98:99], v[98:99], v[72:73] op_sel_hi:[1,1,0]
	v_mov_b32_e32 v110, v113
	v_mov_b32_e32 v116, v112
	v_mov_b32_e32 v74, v114
	v_mov_b32_e32 v72, v115
	v_pk_add_f32 v[110:111], v[116:117], v[110:111]
	v_pk_add_f32 v[72:73], v[74:75], v[72:73]
	s_nop 0
	v_pk_add_f32 v[72:73], v[110:111], v[72:73]
	s_nop 0
	v_add_f32_e32 v72, v72, v73
	ds_bpermute_b32 v73, v66, v72
	s_waitcnt lgkmcnt(0)
	v_add_f32_e32 v72, v72, v73
	ds_bpermute_b32 v73, v67, v72
	s_waitcnt lgkmcnt(0)
	v_add_f32_e32 v72, v72, v73
	ds_bpermute_b32 v73, v68, v72
	s_waitcnt lgkmcnt(0)
	v_add_f32_e32 v72, v72, v73
	ds_bpermute_b32 v73, v69, v72
	s_waitcnt lgkmcnt(0)
	v_add_f32_e32 v72, v72, v73
	ds_bpermute_b32 v73, v70, v72
	s_waitcnt lgkmcnt(0)
	v_add_f32_e32 v72, v72, v73
	ds_bpermute_b32 v73, v71, v72
	s_waitcnt lgkmcnt(0)
	v_add_f32_e32 v72, v72, v73
	v_fmamk_f32 v72, v72, 0x3a000000, v223
	v_cmp_gt_f32_e32 vcc, s62, v72
	v_mul_f32_e32 v73, 0x4f800000, v72
	s_nop 0
	v_cndmask_b32_e32 v72, v72, v73, vcc
	v_sqrt_f32_e32 v73, v72
	s_nop 0
	v_add_u32_e32 v74, -1, v73
	v_fma_f32 v75, -v74, v73, v72
	v_cmp_ge_f32_e64 s[40:41], 0, v75
	v_add_u32_e32 v75, 1, v73
	s_nop 0
	v_cndmask_b32_e64 v74, v73, v74, s[40:41]
	v_fma_f32 v73, -v75, v73, v72
	v_cmp_lt_f32_e64 s[40:41], 0, v73
	s_nop 1
	v_cndmask_b32_e64 v73, v74, v75, s[40:41]
	v_mul_f32_e32 v74, 0x37800000, v73
	v_cndmask_b32_e32 v73, v73, v74, vcc
	v_cmp_class_f32_e32 vcc, v72, v224
	s_nop 1
	v_cndmask_b32_e32 v72, v73, v72, vcc
	v_div_scale_f32 v73, s[0:1], v72, v72, 1.0
	v_rcp_f32_e32 v74, v73
	s_nop 0
	v_fma_f32 v75, -v73, v74, 1.0
	v_fmac_f32_e32 v74, v75, v74
	v_div_scale_f32 v75, vcc, 1.0, v72, 1.0
	v_mul_f32_e32 v110, v75, v74
	v_fma_f32 v111, -v73, v110, v75
	v_fmac_f32_e32 v110, v111, v74
	v_fma_f32 v73, -v73, v110, v75
	v_div_fmas_f32 v73, v73, v74, v110
	v_div_fixup_f32 v110, v73, v72, 1.0
	v_pk_mul_f32 v[72:73], v[86:87], v[110:111] op_sel_hi:[1,0]
	v_pk_mul_f32 v[74:75], v[88:89], v[110:111] op_sel_hi:[1,0]
	v_pk_fma_f32 v[72:73], v[34:35], v[72:73], v[4:5]
	v_add_co_u32_e32 v84, vcc, s26, v84
	v_pk_fma_f32 v[74:75], v[32:33], v[74:75], v[6:7]
	v_pk_mul_f32 v[86:87], v[90:91], v[110:111] op_sel_hi:[1,0]
	v_pk_mul_f32 v[88:89], v[92:93], v[110:111] op_sel_hi:[1,0]
	v_cvt_pk_bf16_f32 v72, v72, v73
	v_cvt_pk_bf16_f32 v73, v74, v75
	v_addc_co_u32_e32 v85, vcc, 0, v85, vcc
	v_pk_fma_f32 v[88:89], v[36:37], v[88:89], v[2:3]
	v_pk_fma_f32 v[86:87], v[38:39], v[86:87], v[0:1]
	s_nop 0
	v_cvt_pk_bf16_f32 v74, v86, v87
	v_cvt_pk_bf16_f32 v75, v88, v89
	global_store_dwordx4 v[84:85], v[72:75], off
	v_pk_mul_f32 v[86:87], v[94:95], v[110:111] op_sel_hi:[1,0]
	v_pk_mul_f32 v[88:89], v[108:109], v[110:111] op_sel_hi:[1,0]
	v_mov_b32_e32 v72, v104
	v_mov_b32_e32 v73, v106
	v_mov_b32_e32 v106, v105
	v_pk_mul_f32 v[72:73], v[72:73], v[110:111] op_sel_hi:[1,0]
	v_pk_mul_f32 v[74:75], v[106:107], v[110:111] op_sel_hi:[1,0]
	v_pk_fma_f32 v[72:73], v[42:43], v[72:73], v[12:13]
	v_pk_fma_f32 v[74:75], v[40:41], v[74:75], v[14:15]
	v_pk_fma_f32 v[88:89], v[44:45], v[88:89], v[10:11]
	v_pk_fma_f32 v[86:87], v[46:47], v[86:87], v[8:9]
	v_cvt_pk_bf16_f32 v72, v72, v73
	v_cvt_pk_bf16_f32 v73, v74, v75
	s_nop 0
	v_cvt_pk_bf16_f32 v74, v86, v87
	v_cvt_pk_bf16_f32 v75, v88, v89
	global_store_dwordx4 v[84:85], v[72:75], off offset:1024
	s_nop 1
	v_pk_mul_f32 v[72:73], v[96:97], v[110:111] op_sel_hi:[1,0]
	v_pk_mul_f32 v[74:75], v[76:77], v[110:111] op_sel_hi:[1,0]
	v_mov_b32_e32 v76, v102
	v_mov_b32_e32 v77, v78
	v_mov_b32_e32 v78, v103
	v_pk_fma_f32 v[74:75], v[48:49], v[74:75], v[22:23]
	v_pk_fma_f32 v[72:73], v[50:51], v[72:73], v[20:21]
	v_pk_mul_f32 v[76:77], v[76:77], v[110:111] op_sel_hi:[1,0]
	v_pk_mul_f32 v[78:79], v[78:79], v[110:111] op_sel_hi:[1,0]
	v_pk_fma_f32 v[76:77], v[54:55], v[76:77], v[16:17]
	v_pk_fma_f32 v[78:79], v[52:53], v[78:79], v[18:19]
	v_cvt_pk_bf16_f32 v72, v72, v73
	v_cvt_pk_bf16_f32 v73, v74, v75
	v_cvt_pk_bf16_f32 v74, v76, v77
	v_pk_mul_f32 v[76:77], v[100:101], v[110:111] op_sel_hi:[1,0]
	v_cvt_pk_bf16_f32 v75, v78, v79
	global_store_dwordx4 v[84:85], v[72:75], off offset:2048
	v_pk_mul_f32 v[78:79], v[82:83], v[110:111] op_sel_hi:[1,0]
	v_pk_fma_f32 v[76:77], v[62:63], v[76:77], v[24:25]
	v_pk_mul_f32 v[72:73], v[98:99], v[110:111] op_sel_hi:[1,0]
	v_pk_mul_f32 v[74:75], v[80:81], v[110:111] op_sel_hi:[1,0]
	v_pk_fma_f32 v[72:73], v[58:59], v[72:73], v[28:29]
	v_pk_fma_f32 v[74:75], v[56:57], v[74:75], v[30:31]
	v_pk_fma_f32 v[78:79], v[60:61], v[78:79], v[26:27]
	v_cvt_pk_bf16_f32 v72, v72, v73
	v_cvt_pk_bf16_f32 v73, v74, v75
	v_cvt_pk_bf16_f32 v74, v76, v77
	s_nop 0
	v_cvt_pk_bf16_f32 v75, v78, v79
	global_store_dwordx4 v[84:85], v[72:75], off offset:3072
	s_cbranch_scc1 .LBB0_291
	v_readlane_b32 s40, v252, 11
	v_readlane_b32 s41, v252, 12
	v_readlane_b32 s42, v252, 13
	v_readlane_b32 s43, v252, 14
	v_readlane_b32 s44, v252, 15
	v_readlane_b32 s45, v252, 16
	v_readlane_b32 s46, v252, 17
	v_readlane_b32 s47, v252, 18

; template <int MODE, bool SRC32>
; __device__ __forceinline__ void phase_mod(const float* x32, _Float16* xh, float* out32, bf16* h, const float* gprev, const float* gain, const float* shiftv, const float* scalev, int wave, int lane) {
;     const int blk = (int)blockIdx.x, b = blk >> 5, r0 = blk * 128 + wave * 16;
;     f32x4 A[8], Sh[8], G3[8];
; #pragma unroll
;     for (int k = 0; k < 8; ++k) {
;         const int d = 512 * (k >> 1) + 8 * lane + 4 * (k & 1);
;         if (MODE != 2) { const f32x4 g = *(const f32x4*)(gain + d), sc = *(const f32x4*)(scalev + (size_t)b * NMOD + d); A[k] = g * (sc + 1.0f); Sh[k] = *(const f32x4*)(shiftv + (size_t)b * NMOD + d); }
;         if (MODE != 0) G3[k] = *(const f32x4*)(gprev + d);
;     }
;     for (int i = 0; i < 16; ++i) {
;         const size_t ro = (size_t)(r0 + i) * D + 8 * lane;
.LBB0_945:
	s_cmp_le_i32 s44, s18
	s_cselect_b64 s[0:1], -1, 0
	s_cmp_lt_i32 s18, s45
	s_cselect_b64 s[4:5], -1, 0
	s_and_b64 s[4:5], s[0:1], s[4:5]
	s_andn2_b64 vcc, exec, s[4:5]
	v_readfirstlane_b32 s0, v214
	s_cbranch_vccnz .LBB0_949
	s_ashr_i32 s0, s0, 2
	s_and_b32 s0, s0, -16
	v_readlane_b32 s1, v253, 7
	s_add_i32 s6, s0, s1
	v_readlane_b32 s0, v254, 44
	v_readlane_b32 s1, v254, 45
	s_lshl_b64 s[0:1], s[0:1], 2
	s_add_u32 s2, s20, s0
	s_addc_u32 s7, s21, s1
	s_add_u32 s0, s2, 0xc000
	s_addc_u32 s1, s7, 0
	s_add_u32 s8, s2, 0xe000
	s_addc_u32 s9, s7, 0
	v_readlane_b32 s10, v255, 2
	v_readlane_b32 s11, v255, 3
	s_add_u32 s10, s10, 0x4000
	s_waitcnt vmcnt(0)
	v_lshlrev_b32_e32 v0, 5, v214
	s_addc_u32 s11, s11, 0
	v_and_b32_e32 v24, 0x7e0, v0
	global_load_dwordx4 v[8:11], v24, s[10:11] offset:16
	global_load_dwordx4 v[0:3], v24, s[10:11]
	global_load_dwordx4 v[12:15], v24, s[8:9] offset:16
	global_load_dwordx4 v[4:7], v24, s[8:9]
	v_or_b32_e32 v20, 0x800, v24
	v_or_b32_e32 v52, 0x1000, v24
	v_or_b32_e32 v60, 0x1800, v24
	v_cmp_lt_i32_e32 vcc, v222, v216
	s_ashr_i32 s7, s6, 31
	s_waitcnt vmcnt(1)
	v_pk_add_f32 v[14:15], v[14:15], 1.0 op_sel_hi:[1,0]
	s_waitcnt vmcnt(0)
	v_pk_add_f32 v[6:7], v[6:7], 1.0 op_sel_hi:[1,0]
	v_pk_add_f32 v[4:5], v[4:5], 1.0 op_sel_hi:[1,0]
	v_pk_add_f32 v[12:13], v[12:13], 1.0 op_sel_hi:[1,0]
	v_pk_mul_f32 v[32:33], v[2:3], v[6:7]
	v_pk_mul_f32 v[34:35], v[0:1], v[4:5]
	global_load_dwordx4 v[0:3], v24, s[0:1] offset:16
	global_load_dwordx4 v[4:7], v24, s[0:1]
	v_pk_mul_f32 v[36:37], v[10:11], v[14:15]
	v_pk_mul_f32 v[38:39], v[8:9], v[12:13]
	global_load_dwordx4 v[16:19], v20, s[10:11] offset:16
	global_load_dwordx4 v[8:11], v20, s[10:11]
	s_nop 0
	global_load_dwordx4 v[20:23], v24, s[8:9] offset:2064
	global_load_dwordx4 v[12:15], v24, s[8:9] offset:2048
	s_waitcnt vmcnt(1)
	v_pk_add_f32 v[22:23], v[22:23], 1.0 op_sel_hi:[1,0]
	s_waitcnt vmcnt(0)
	v_pk_add_f32 v[14:15], v[14:15], 1.0 op_sel_hi:[1,0]
	v_pk_add_f32 v[12:13], v[12:13], 1.0 op_sel_hi:[1,0]
	v_pk_add_f32 v[20:21], v[20:21], 1.0 op_sel_hi:[1,0]
	v_pk_mul_f32 v[40:41], v[10:11], v[14:15]
	v_pk_mul_f32 v[42:43], v[8:9], v[12:13]
	global_load_dwordx4 v[8:11], v24, s[0:1] offset:2064
	global_load_dwordx4 v[12:15], v24, s[0:1] offset:2048
	v_pk_mul_f32 v[44:45], v[18:19], v[22:23]
	v_pk_mul_f32 v[46:47], v[16:17], v[20:21]
	global_load_dwordx4 v[24:27], v52, s[10:11] offset:16
	global_load_dwordx4 v[16:19], v52, s[10:11]
	global_load_dwordx4 v[28:31], v52, s[8:9] offset:16
	global_load_dwordx4 v[20:23], v52, s[8:9]
	s_waitcnt vmcnt(1)
	v_pk_add_f32 v[30:31], v[30:31], 1.0 op_sel_hi:[1,0]
	s_waitcnt vmcnt(0)
	v_pk_add_f32 v[22:23], v[22:23], 1.0 op_sel_hi:[1,0]
	v_pk_add_f32 v[20:21], v[20:21], 1.0 op_sel_hi:[1,0]
	v_pk_add_f32 v[28:29], v[28:29], 1.0 op_sel_hi:[1,0]
	v_pk_mul_f32 v[48:49], v[18:19], v[22:23]
	v_pk_mul_f32 v[50:51], v[16:17], v[20:21]
	global_load_dwordx4 v[16:19], v52, s[0:1] offset:16
	global_load_dwordx4 v[20:23], v52, s[0:1]
	v_pk_mul_f32 v[52:53], v[26:27], v[30:31]
	v_pk_mul_f32 v[54:55], v[24:25], v[28:29]
	global_load_dwordx4 v[62:65], v60, s[10:11] offset:16
	global_load_dwordx4 v[24:27], v60, s[10:11]
	global_load_dwordx4 v[66:69], v60, s[8:9] offset:16
	global_load_dwordx4 v[28:31], v60, s[8:9]
	s_waitcnt vmcnt(1)
	v_pk_add_f32 v[66:67], v[66:67], 1.0 op_sel_hi:[1,0]
	s_waitcnt vmcnt(0)
	v_pk_add_f32 v[30:31], v[30:31], 1.0 op_sel_hi:[1,0]
	v_pk_add_f32 v[28:29], v[28:29], 1.0 op_sel_hi:[1,0]
	v_pk_mul_f32 v[56:57], v[26:27], v[30:31]
	v_pk_mul_f32 v[58:59], v[24:25], v[28:29]
	global_load_dwordx4 v[24:27], v60, s[0:1] offset:16
	global_load_dwordx4 v[28:31], v60, s[0:1]
	v_pk_add_f32 v[60:61], v[68:69], 1.0 op_sel_hi:[1,0]
	v_pk_mul_f32 v[62:63], v[62:63], v[66:67]
	v_pk_mul_f32 v[60:61], v[64:65], v[60:61]
	v_cndmask_b32_e32 v64, v215, v222, vcc
	v_cmp_lt_i32_e32 vcc, v221, v216
	v_lshlrev_b32_e32 v66, 2, v64
	s_lshl_b64 s[0:1], s[6:7], 12
	v_cndmask_b32_e32 v64, v215, v221, vcc
	v_cmp_lt_i32_e32 vcc, v220, v216
	v_lshlrev_b32_e32 v67, 2, v64
	s_add_u32 s0, s42, s0
	v_cndmask_b32_e32 v64, v215, v220, vcc
	v_cmp_lt_i32_e32 vcc, v219, v216
	v_lshlrev_b32_e32 v68, 2, v64
	s_addc_u32 s1, s43, s1
	v_cndmask_b32_e32 v64, v215, v219, vcc
	v_cmp_lt_i32_e32 vcc, v218, v216
	v_lshlrev_b32_e32 v69, 2, v64
	s_mov_b64 s[6:7], 0
	v_cndmask_b32_e32 v64, v215, v218, vcc
	v_cmp_lt_i32_e32 vcc, v217, v216
	v_lshlrev_b32_e32 v70, 2, v64
	s_nop 0
	v_cndmask_b32_e32 v64, v215, v217, vcc
	v_lshlrev_b32_e32 v71, 2, v64
	v_and_b32_e32 v64, 63, v214
	v_lshlrev_b32_e32 v168, 4, v64
	v_lshl_add_u64 v[64:65], s[0:1], 0, v[168:169]
	v_add_co_u32_e32 v136, vcc, 0x4ae00000, v64
	v_mov_b32_e32 v138, 0x1000
	v_mov_b32_e32 v139, 0
	v_addc_co_u32_e32 v137, vcc, 0, v65, vcc
	global_load_dwordx4 v[120:123], v[136:137], off
	global_load_dwordx4 v[128:131], v[136:137], off offset:2048
	global_load_dwordx4 v[124:127], v[136:137], off offset:1024
	global_load_dwordx4 v[132:135], v[136:137], off offset:3072
	s_waitcnt vmcnt(0)
; template <int MODE, bool SRC32>
; __device__ __forceinline__ void phase_mod(const float* x32, _Float16* xh, float* out32, bf16* h, const float* gprev, const float* gain, const float* shiftv, const float* scalev, int wave, int lane) {
;     ...
;     for (int i = 0; i < 16; ++i) {
;         const size_t ro = (size_t)(r0 + i) * D + 8 * lane;
;         f32x4 v[8]; float ss = 0.f;
; #pragma unroll
;         for (int j = 0; j < 4; ++j) {
;             if (SRC32) { v[2 * j] = *(const f32x4*)(x32 + ro + 512 * j); v[2 * j + 1] = *(const f32x4*)(x32 + ro + 512 * j + 4); }
;             else h8_to_f(*(const h16x8*)(xh + ro + 512 * j), v[2 * j], v[2 * j + 1]);
;         }
; #pragma unroll
;         for (int k = 0; k < 8; ++k) ss += (v[k][0] * v[k][0] + v[k][1] * v[k][1]) + (v[k][2] * v[k][2] + v[k][3] * v[k][3]);
.LBB0_947:
	v_lshl_add_u64 v[84:85], v[64:65], 0, s[6:7]
	s_add_u32 s6, s6, 0x1000
	s_addc_u32 s7, s7, 0
	s_cmp_lg_u32 s6, 0x10000
	s_waitcnt vmcnt(7)
	v_cvt_f32_f16_e32 v86, v120
	v_cvt_f32_f16_sdwa v87, v120 dst_sel:DWORD dst_unused:UNUSED_PAD src0_sel:WORD_1
	v_cvt_f32_f16_e32 v88, v121
	v_cvt_f32_f16_sdwa v89, v121 dst_sel:DWORD dst_unused:UNUSED_PAD src0_sel:WORD_1
	v_cvt_f32_f16_e32 v90, v122
	v_cvt_f32_f16_sdwa v91, v122 dst_sel:DWORD dst_unused:UNUSED_PAD src0_sel:WORD_1
	v_cvt_f32_f16_e32 v92, v123
	v_cvt_f32_f16_sdwa v93, v123 dst_sel:DWORD dst_unused:UNUSED_PAD src0_sel:WORD_1
	v_mov_b32_e32 v104, v87
	v_mov_b32_e32 v105, v91
	v_mov_b32_e32 v102, v86
	v_mov_b32_e32 v103, v90
	v_pk_mul_f32 v[104:105], v[104:105], v[104:105]
	v_mov_b32_e32 v106, v89
	v_mov_b32_e32 v107, v93
	v_pk_fma_f32 v[102:103], v[102:103], v[102:103], v[104:105]
	v_mov_b32_e32 v104, v88
	v_mov_b32_e32 v105, v92
	v_pk_mul_f32 v[106:107], v[106:107], v[106:107]
	s_waitcnt vmcnt(6)
	v_cvt_f32_f16_e32 v96, v128
	v_pk_fma_f32 v[104:105], v[104:105], v[104:105], v[106:107]
	v_cvt_f32_f16_sdwa v97, v128 dst_sel:DWORD dst_unused:UNUSED_PAD src0_sel:WORD_1
	v_pk_add_f32 v[102:103], v[102:103], v[104:105]
	v_cvt_f32_f16_e32 v76, v129
	v_cvt_f32_f16_sdwa v77, v129 dst_sel:DWORD dst_unused:UNUSED_PAD src0_sel:WORD_1
	v_pk_add_f32 v[102:103], v[102:103], v[102:103] op_sel_hi:[0,1]
	v_pk_mul_f32 v[110:111], v[96:97], v[96:97]
	v_pk_mul_f32 v[112:113], v[76:77], v[76:77]
	s_nop 0
	v_mov_b32_e32 v102, v112
	s_waitcnt vmcnt(5)
	v_cvt_f32_f16_sdwa v107, v125 dst_sel:DWORD dst_unused:UNUSED_PAD src0_sel:WORD_1
	v_cvt_f32_f16_sdwa v106, v124 dst_sel:DWORD dst_unused:UNUSED_PAD src0_sel:WORD_1
	v_cvt_f32_f16_e32 v105, v125
	v_cvt_f32_f16_e32 v104, v124
	v_cvt_f32_f16_e32 v108, v127
	v_cvt_f32_f16_e32 v94, v126
	v_pk_mul_f32 v[72:73], v[106:107], v[106:107]
	v_cvt_f32_f16_sdwa v109, v127 dst_sel:DWORD dst_unused:UNUSED_PAD src0_sel:WORD_1
	v_cvt_f32_f16_sdwa v95, v126 dst_sel:DWORD dst_unused:UNUSED_PAD src0_sel:WORD_1
	v_pk_fma_f32 v[72:73], v[104:105], v[104:105], v[72:73]
	s_waitcnt vmcnt(4)
	v_cvt_f32_f16_e32 v98, v132
	v_pk_add_f32 v[72:73], v[72:73], v[72:73] op_sel_hi:[0,1]
	v_mul_f32_e32 v72, v108, v108
	v_pk_fma_f32 v[74:75], v[108:109], v[108:109], v[72:73] op_sel_hi:[1,1,0]
	v_mul_f32_e32 v72, v94, v94
	v_pk_fma_f32 v[114:115], v[94:95], v[94:95], v[72:73] op_sel_hi:[1,1,0]
	v_mov_b32_e32 v72, v113
	v_cvt_f32_f16_sdwa v99, v132 dst_sel:DWORD dst_unused:UNUSED_PAD src0_sel:WORD_1
	v_mov_b32_e32 v114, v110
	v_mov_b32_e32 v74, v111
	v_pk_add_f32 v[72:73], v[102:103], v[72:73]
	v_cvt_f32_f16_e32 v103, v131
	v_cvt_f32_f16_e32 v102, v130
	v_cvt_f32_f16_sdwa v79, v131 dst_sel:DWORD dst_unused:UNUSED_PAD src0_sel:WORD_1
	v_cvt_f32_f16_sdwa v78, v130 dst_sel:DWORD dst_unused:UNUSED_PAD src0_sel:WORD_1
	v_cvt_f32_f16_e32 v80, v133
	v_pk_add_f32 v[74:75], v[114:115], v[74:75]
	v_cvt_f32_f16_sdwa v81, v133 dst_sel:DWORD dst_unused:UNUSED_PAD src0_sel:WORD_1
	v_cvt_f32_f16_e32 v100, v134
	v_cvt_f32_f16_sdwa v101, v134 dst_sel:DWORD dst_unused:UNUSED_PAD src0_sel:WORD_1
	v_cvt_f32_f16_e32 v82, v135
	v_cvt_f32_f16_sdwa v83, v135 dst_sel:DWORD dst_unused:UNUSED_PAD src0_sel:WORD_1
	s_cbranch_scc0 .Lmodpf_c_skip
	v_lshl_add_u64 v[136:137], v[136:137], 0, v[138:139]
	global_load_dwordx4 v[120:123], v[136:137], off
	global_load_dwordx4 v[128:131], v[136:137], off offset:2048
	global_load_dwordx4 v[124:127], v[136:137], off offset:1024
	global_load_dwordx4 v[132:135], v[136:137], off offset:3072
; __device__ __forceinline__ unsigned cvt_pk_bf16(float lo, float hi) { unsigned r; asm volatile("v_cvt_pk_bf16_f32 %0, %1, %2" : "=v"(r) : "v"(lo), "v"(hi)); return r; }
; __device__ __forceinline__ h16x8 f_to_h8(const f32x4 a, const f32x4 b) { return (h16x8){(_Float16)a[0], (_Float16)a[1], (_Float16)a[2], (_Float16)a[3], (_Float16)b[0], (_Float16)b[1], (_Float16)b[2], (_Float16)b[3]}; }
; template <int MODE, bool SRC32>
; __device__ __forceinline__ void phase_mod(const float* x32, _Float16* xh, float* out32, bf16* h, const float* gprev, const float* gain, const float* shiftv, const float* scalev, int wave, int lane) {
;     ...
;         for (int k = 0; k < 8; ++k) ss += (v[k][0] * v[k][0] + v[k][1] * v[k][1]) + (v[k][2] * v[k][2] + v[k][3] * v[k][3]);
;         ss = wave_sum(ss);
;         float rstd = 1.0f / sqrtf(ss * (1.0f / D) + EPS);
;         if (MODE != 0) {
;             float s2 = 0.f;
; #pragma unroll
;             for (int k = 0; k < 8; ++k) { v[k] = v[k] * rstd * G3[k]; s2 += (v[k][0] * v[k][0] + v[k][1] * v[k][1]) + (v[k][2] * v[k][2] + v[k][3] * v[k][3]); }
; #pragma unroll
;             for (int j = 0; j < 4; ++j) {
;                 if (MODE == 1) *(h16x8*)(xh + ro + 512 * j) = f_to_h8(v[2 * j], v[2 * j + 1]);
;                 else { *(f32x4*)(out32 + ro + 512 * j) = v[2 * j]; *(f32x4*)(out32 + ro + 512 * j + 4) = v[2 * j + 1]; }
;             }
;             if (MODE == 2) continue;
;             s2 = wave_sum(s2);
;             rstd = 1.0f / sqrtf(s2 * (1.0f / D) + EPS);
;         }
; #pragma unroll
;         for (int j = 0; j < 4; ++j) { const f32x4 o0 = v[2 * j] * rstd * A[2 * j] + Sh[2 * j], o1 = v[2 * j + 1] * rstd * A[2 * j + 1] + Sh[2 * j + 1];
;             u32x4 w; w.x = cvt_pk_bf16(o0[0], o0[1]); w.y = cvt_pk_bf16(o0[2], o0[3]); w.z = cvt_pk_bf16(o1[0], o1[1]); w.w = cvt_pk_bf16(o1[2], o1[3]);
;             *(u32x4*)(h + ro + 512 * j) = w; }
;     }
.Lmodpf_c_skip:
	v_pk_add_f32 v[72:73], v[74:75], v[72:73]
	v_pk_mul_f32 v[74:75], v[78:79], v[78:79]
	v_pk_add_f32 v[72:73], v[72:73], v[72:73] op_sel_hi:[0,1]
	v_mul_f32_e32 v72, v80, v80
	v_pk_fma_f32 v[74:75], v[102:103], v[102:103], v[74:75]
	v_pk_fma_f32 v[110:111], v[80:81], v[80:81], v[72:73] op_sel_hi:[1,1,0]
	v_mul_f32_e32 v72, v98, v98
	v_pk_add_f32 v[74:75], v[74:75], v[74:75] op_sel_hi:[0,1]
	v_pk_mul_f32 v[112:113], v[100:101], v[100:101]
	v_pk_mul_f32 v[114:115], v[82:83], v[82:83]
	v_pk_fma_f32 v[116:117], v[98:99], v[98:99], v[72:73] op_sel_hi:[1,1,0]
	v_mov_b32_e32 v110, v113
	v_mov_b32_e32 v116, v112
	v_mov_b32_e32 v74, v114
	v_mov_b32_e32 v72, v115
	v_pk_add_f32 v[110:111], v[116:117], v[110:111]
	v_pk_add_f32 v[72:73], v[74:75], v[72:73]
	s_nop 0
	v_pk_add_f32 v[72:73], v[110:111], v[72:73]
	s_nop 0
	v_add_f32_e32 v72, v72, v73
	ds_bpermute_b32 v73, v66, v72
	s_waitcnt lgkmcnt(0)
	v_add_f32_e32 v72, v72, v73
	ds_bpermute_b32 v73, v67, v72
	s_waitcnt lgkmcnt(0)
	v_add_f32_e32 v72, v72, v73
	ds_bpermute_b32 v73, v68, v72
	s_waitcnt lgkmcnt(0)
	v_add_f32_e32 v72, v72, v73
	ds_bpermute_b32 v73, v69, v72
	s_waitcnt lgkmcnt(0)
	v_add_f32_e32 v72, v72, v73
	ds_bpermute_b32 v73, v70, v72
	s_waitcnt lgkmcnt(0)
	v_add_f32_e32 v72, v72, v73
	ds_bpermute_b32 v73, v71, v72
	s_waitcnt lgkmcnt(0)
	v_add_f32_e32 v72, v72, v73
	v_fmamk_f32 v72, v72, 0x3a000000, v223
	v_cmp_gt_f32_e32 vcc, s62, v72
	v_mul_f32_e32 v73, 0x4f800000, v72
	s_nop 0
	v_cndmask_b32_e32 v72, v72, v73, vcc
	v_sqrt_f32_e32 v73, v72
	s_nop 0
	v_add_u32_e32 v74, -1, v73
	v_fma_f32 v75, -v74, v73, v72
	v_cmp_ge_f32_e64 s[40:41], 0, v75
	v_add_u32_e32 v75, 1, v73
	s_nop 0
	v_cndmask_b32_e64 v74, v73, v74, s[40:41]
	v_fma_f32 v73, -v75, v73, v72
	v_cmp_lt_f32_e64 s[40:41], 0, v73
	s_nop 1
	v_cndmask_b32_e64 v73, v74, v75, s[40:41]
	v_mul_f32_e32 v74, 0x37800000, v73
	v_cndmask_b32_e32 v73, v73, v74, vcc
	v_cmp_class_f32_e32 vcc, v72, v224
	s_nop 1
	v_cndmask_b32_e32 v72, v73, v72, vcc
	v_div_scale_f32 v73, s[0:1], v72, v72, 1.0
	v_rcp_f32_e32 v74, v73
	s_nop 0
	v_fma_f32 v75, -v73, v74, 1.0
	v_fmac_f32_e32 v74, v75, v74
	v_div_scale_f32 v75, vcc, 1.0, v72, 1.0
	v_mul_f32_e32 v110, v75, v74
	v_fma_f32 v111, -v73, v110, v75
	v_fmac_f32_e32 v110, v111, v74
	v_fma_f32 v73, -v73, v110, v75
	v_div_fmas_f32 v73, v73, v74, v110
	v_div_fixup_f32 v110, v73, v72, 1.0
	v_pk_mul_f32 v[72:73], v[86:87], v[110:111] op_sel_hi:[1,0]
	v_pk_mul_f32 v[74:75], v[88:89], v[110:111] op_sel_hi:[1,0]
	v_pk_fma_f32 v[72:73], v[34:35], v[72:73], v[4:5]
	v_add_co_u32_e32 v84, vcc, s26, v84
	v_pk_fma_f32 v[74:75], v[32:33], v[74:75], v[6:7]
	v_pk_mul_f32 v[86:87], v[90:91], v[110:111] op_sel_hi:[1,0]
	v_pk_mul_f32 v[88:89], v[92:93], v[110:111] op_sel_hi:[1,0]
	v_cvt_pk_bf16_f32 v72, v72, v73
	v_cvt_pk_bf16_f32 v73, v74, v75
	v_addc_co_u32_e32 v85, vcc, 0, v85, vcc
	v_pk_fma_f32 v[88:89], v[36:37], v[88:89], v[2:3]
	v_pk_fma_f32 v[86:87], v[38:39], v[86:87], v[0:1]
	s_nop 0
	v_cvt_pk_bf16_f32 v74, v86, v87
	v_cvt_pk_bf16_f32 v75, v88, v89
	global_store_dwordx4 v[84:85], v[72:75], off
	v_pk_mul_f32 v[86:87], v[94:95], v[110:111] op_sel_hi:[1,0]
	v_pk_mul_f32 v[88:89], v[108:109], v[110:111] op_sel_hi:[1,0]
	v_mov_b32_e32 v72, v104
	v_mov_b32_e32 v73, v106
	v_mov_b32_e32 v106, v105
	v_pk_mul_f32 v[72:73], v[72:73], v[110:111] op_sel_hi:[1,0]
	v_pk_mul_f32 v[74:75], v[106:107], v[110:111] op_sel_hi:[1,0]
	v_pk_fma_f32 v[72:73], v[42:43], v[72:73], v[12:13]
	v_pk_fma_f32 v[74:75], v[40:41], v[74:75], v[14:15]
	v_pk_fma_f32 v[88:89], v[44:45], v[88:89], v[10:11]
	v_pk_fma_f32 v[86:87], v[46:47], v[86:87], v[8:9]
	v_cvt_pk_bf16_f32 v72, v72, v73
	v_cvt_pk_bf16_f32 v73, v74, v75
	s_nop 0
	v_cvt_pk_bf16_f32 v74, v86, v87
	v_cvt_pk_bf16_f32 v75, v88, v89
	global_store_dwordx4 v[84:85], v[72:75], off offset:1024
	s_nop 1
	v_pk_mul_f32 v[72:73], v[96:97], v[110:111] op_sel_hi:[1,0]
	v_pk_mul_f32 v[74:75], v[76:77], v[110:111] op_sel_hi:[1,0]
	v_mov_b32_e32 v76, v102
	v_mov_b32_e32 v77, v78
	v_mov_b32_e32 v78, v103
	v_pk_fma_f32 v[74:75], v[48:49], v[74:75], v[22:23]
	v_pk_fma_f32 v[72:73], v[50:51], v[72:73], v[20:21]
	v_pk_mul_f32 v[76:77], v[76:77], v[110:111] op_sel_hi:[1,0]
	v_pk_mul_f32 v[78:79], v[78:79], v[110:111] op_sel_hi:[1,0]
	v_pk_fma_f32 v[76:77], v[54:55], v[76:77], v[16:17]
	v_pk_fma_f32 v[78:79], v[52:53], v[78:79], v[18:19]
	v_cvt_pk_bf16_f32 v72, v72, v73
	v_cvt_pk_bf16_f32 v73, v74, v75
	v_cvt_pk_bf16_f32 v74, v76, v77
	v_pk_mul_f32 v[76:77], v[100:101], v[110:111] op_sel_hi:[1,0]
	v_cvt_pk_bf16_f32 v75, v78, v79
	global_store_dwordx4 v[84:85], v[72:75], off offset:2048
	v_pk_mul_f32 v[78:79], v[82:83], v[110:111] op_sel_hi:[1,0]
	v_pk_fma_f32 v[76:77], v[62:63], v[76:77], v[24:25]
	v_pk_mul_f32 v[72:73], v[98:99], v[110:111] op_sel_hi:[1,0]
	v_pk_mul_f32 v[74:75], v[80:81], v[110:111] op_sel_hi:[1,0]
	v_pk_fma_f32 v[72:73], v[58:59], v[72:73], v[28:29]
	v_pk_fma_f32 v[74:75], v[56:57], v[74:75], v[30:31]
	v_pk_fma_f32 v[78:79], v[60:61], v[78:79], v[26:27]
	v_cvt_pk_bf16_f32 v72, v72, v73
	v_cvt_pk_bf16_f32 v73, v74, v75
	v_cvt_pk_bf16_f32 v74, v76, v77
	s_nop 0
	v_cvt_pk_bf16_f32 v75, v78, v79
	global_store_dwordx4 v[84:85], v[72:75], off offset:3072
	s_cbranch_scc1 .LBB0_947
	v_readlane_b32 s40, v252, 11
	v_readlane_b32 s41, v252, 12
	v_readlane_b32 s42, v252, 13
	v_readlane_b32 s43, v252, 14
	v_readlane_b32 s44, v252, 15
	v_readlane_b32 s45, v252, 16
	v_readlane_b32 s2, v255, 7
	v_readlane_b32 s46, v252, 17
	v_readlane_b32 s47, v252, 18
